# MIX2 HGRN2 state scan: the scan workgroup touches the lines of its later chunks up front so the later load batches are served from L2
# baseline (speedup 1.0000x reference)
.LBB0_295:
	s_cmp_lt_i32 s94, 64
	s_cselect_b64 s[8:9], -1, 0
	s_cmp_gt_i32 s94, 63
	s_cbranch_scc1 .LBB0_298
	s_lshl_b32 s4, s94, 9
	s_and_b32 s4, s4, 0x600
	v_mov_b32_e32 v0, v244
	s_ashr_i32 s3, s94, 2
	s_waitcnt vmcnt(0)
	v_add_u32_e32 v4, s4, v0
	v_ashrrev_i32_e32 v5, 31, v4
	v_lshlrev_b64 v[2:3], 2, v[4:5]
	v_mov_b32_e32 v0, 0x108000
	s_mul_hi_i32 s10, s3, 0x8400
	s_mul_i32 s11, s3, 0x8400
	v_mad_i64_i32 v[2:3], s[4:5], s3, v0, v[2:3]
	v_and_b32_e32 v0, 31, v4
	v_mov_b32_e32 v6, 0
	v_lshl_or_b32 v4, v0, 3, s11
	v_mov_b32_e32 v5, s10
	s_movk_i32 s3, 0xffdf
	v_mov_b32_e32 v7, v6
	v_and_b32_e32 v229, 31, v244
	v_lshrrev_b32_e32 v230, 5, v244
	v_lshlrev_b32_e32 v231, 2, v244
	v_lshlrev_b32_e32 v229, 6, v229
	v_lshl_add_u32 v229, v230, 13, v229
	v_sub_u32_e32 v229, v229, v231
	v_add_u32_e32 v229, v229, v2
	v_add_u32_e32 v229, 0xd042000, v229
	global_load_dword v220, v229, s[96:97]
	v_add_u32_e32 v229, 0x20000, v229
	global_load_dword v221, v229, s[96:97]
	v_add_u32_e32 v229, 0x20000, v229
	global_load_dword v222, v229, s[96:97]
	v_add_u32_e32 v229, 0x20000, v229
	global_load_dword v223, v229, s[96:97]
	v_add_u32_e32 v229, 0x20000, v229
	global_load_dword v224, v229, s[96:97]
	v_add_u32_e32 v229, 0x20000, v229
	global_load_dword v225, v229, s[96:97]
	v_add_u32_e32 v229, 0x20000, v229
	global_load_dword v226, v229, s[96:97]
